# scan loop: removed redundant hazard s_nop between inline-asm FMAs and 5 over-conservative vmcnt waits (WAW on registers whose loads had already been consumed)
# speedup vs baseline: 1.0287x; 1.0287x over previous
; __device__ __forceinline__ void even_scan(const Params& p, int j, LAS unsigned char* lds, int gw, int NGW, int wave, int lane) {
;     ...
;         for (int st = 0; st < nst; ++st) {
;             const bool more = st + 1 < nst;
;             if (more) { const size_t o = base + (size_t)((st + 1) * TS + ls) * 512 + lq;
;                 rg[0] = *(const f32x4*)(A0 + o); rg[1] = *(const f32x4*)(A1 + o); rg[2] = *(const f32x4*)(A2 + o); rg[3] = *(const f32x4*)(A3 + o); rg[4] = *(const f32x4*)(A4 + o); rg[5] = *(const f32x4*)(A5 + o); }
.LBB0_1327:
	s_add_i32 s43, s12, 1
	s_cmp_lt_u32 s43, s34
	s_cselect_b64 s[2:3], -1, 0
	s_cmp_ge_u32 s43, s34
	s_cbranch_scc1 .LBB0_1329
	v_lshl_add_u32 v184, s43, 2, v229
	v_lshlrev_b64 v[136:137], 9, v[184:185]
	v_lshl_add_u64 v[136:137], v[136:137], 0, v[204:205]
	v_lshlrev_b64 v[152:153], 2, v[136:137]
	v_lshl_add_u64 v[136:137], s[68:69], 0, v[152:153]
	v_lshl_add_u64 v[140:141], s[72:73], 0, v[152:153]
	v_lshl_add_u64 v[144:145], s[74:75], 0, v[152:153]
	v_lshl_add_u64 v[148:149], s[76:77], 0, v[152:153]
	v_lshl_add_u64 v[154:155], s[66:67], 0, v[152:153]
	v_lshl_add_u64 v[156:157], s[92:93], 0, v[152:153]
	global_load_dwordx4 v[136:139], v[136:137], off
	s_nop 0
	global_load_dwordx4 v[140:143], v[140:141], off
	s_nop 0
	global_load_dwordx4 v[144:147], v[144:145], off
	s_nop 0
	global_load_dwordx4 v[148:151], v[148:149], off
	s_nop 0
	global_load_dwordx4 v[152:155], v[154:155], off
	s_nop 0
	global_load_dwordx4 v[156:159], v[156:157], off

; #define LAS __attribute__((address_space(3)))
; __device__ __forceinline__ void swap16_(float& a, float& b) { asm volatile("s_nop 1\n\tv_permlane16_swap_b32 %0, %1" : "+v"(a), "+v"(b)); }
; __device__ __forceinline__ void swap32_(float& a, float& b) { asm volatile("s_nop 1\n\tv_permlane32_swap_b32 %0, %1" : "+v"(a), "+v"(b)); }
; __device__ __forceinline__ void even_scan(const Params& p, int j, LAS unsigned char* lds, int gw, int NGW, int wave, int lane) {
;     ...
;             for (int s = 0; s < TS; ++s) {
;                 const LAS float* sb = bb + s * 384 + cq * 16;
;                 f32x4 cbuf[CPS];
; #pragma unroll
;                 for (int c = 0; c < CPS; ++c) { const int li = cli + c * NGW * 64;
;                     if (li < KVC_N2 && ((li >> 8) & 2047) >= 8) cbuf[c] = __builtin_nontemporal_load(csrc + c * NGW * 64); }
;                 float saL[4], saP[4];
; #pragma unroll
;                 for (int rr = 0; rr < 4; ++rr) { saL[rr] = 0.f; saP[rr] = 0.f; }
; #pragma unroll
;                 for (int c = 0; c < 16; c += 4) { const f32x4 k4 = *(const LAS f32x4*)(sb + c);
; #pragma unroll
;                     for (int rr = 0; rr < 4; ++rr)
; #pragma unroll
;                         for (int e = 0; e < 4; ++e) { saL[rr] = fnma_s(SL[rr][c + e], k4[e], saL[rr]); saP[rr] = fnma_s(SP[rr][c + e], k4[e], saP[rr]); } }
;                 float vv[4];
; #pragma unroll
;                 for (int rr = 0; rr < 4; ++rr) { vv[rr] = bb[s * 384 + 320 + i16 + 16 * rr];
;                 }
;                 {
;                     float a = saL[0], b = saL[1], c = saL[2], d = saL[3]; swap16_(a, b); swap16_(c, d); float s01 = a + b, s23 = c + d; swap32_(s01, s23); const float T = s01 + s23;
;                     float u = T, w = T; swap16_(u, w); float x0 = u, x2 = u, x1 = w, x3 = w; swap32_(x0, x2); swap32_(x1, x3); saL[0] = x0; saL[1] = x1; saL[2] = x2; saL[3] = x3;
;                 }
;                 {
;                     float a = saP[0], b = saP[1], c = saP[2], d = saP[3]; swap16_(a, b); swap16_(c, d); float s01 = a + b, s23 = c + d; swap32_(s01, s23); const float T = s01 + s23;
;                     float u = T, w = T; swap16_(u, w); float x0 = u, x2 = u, x1 = w, x3 = w; swap32_(x0, x2); swap32_(x1, x3); saP[0] = x0; saP[1] = x1; saP[2] = x2; saP[3] = x3;
;                 }
.LBB0_1331:
	v_and_b32_e32 v161, 0x7f800, v160
	v_cmp_gt_i32_e32 vcc, s4, v160
	v_cmp_ne_u32_e64 s[36:37], 0, v161
	s_and_b64 s[26:27], vcc, s[36:37]
	s_and_saveexec_b64 s[24:25], s[26:27]
	s_cbranch_execz .LBB0_1333
	v_lshl_add_u64 v[4:5], v[192:193], 0, s[12:13]
	global_load_dwordx4 v[4:7], v[4:5], off nt
.LBB0_1333:
	s_or_b64 exec, exec, s[24:25]
	v_add_u32_e32 v235, s18, v160
	v_and_b32_e32 v160, 0x7f800, v235
	v_cmp_gt_i32_e32 vcc, s4, v235
	v_cmp_ne_u32_e64 s[36:37], 0, v160
	s_and_b64 s[30:31], vcc, s[36:37]
	s_and_saveexec_b64 s[24:25], s[30:31]
	s_cbranch_execz .LBB0_1335
	v_lshl_add_u64 v[0:1], v[210:211], 0, s[12:13]
	global_load_dwordx4 v[0:3], v[0:1], off nt
.LBB0_1335:
	s_or_b64 exec, exec, s[24:25]
	ds_read_b128 v[168:171], v234
	ds_read_b128 v[172:175], v234 offset:16
	ds_read_b128 v[164:167], v234 offset:32
	ds_read_b128 v[160:163], v234 offset:48
	ds_read2_b32 v[218:219], v184 offset1:16
	ds_read2_b32 v[216:217], v184 offset0:32 offset1:48
	s_waitcnt lgkmcnt(5)
	v_fma_f32 v176, -v80, v168, v185
	v_fma_f32 v177, -v132, v168, v185
	v_fma_f32 v178, -v52, v168, v185
	v_fma_f32 v179, -v116, v168, v185
	v_fma_f32 v180, -v36, v168, v185
	v_fma_f32 v181, -v100, v168, v185
	v_fma_f32 v176, -v81, v169, v176
	v_fma_f32 v182, -v16, v168, v185
	v_fma_f32 v168, -v84, v168, v185
	v_fma_f32 v177, -v133, v169, v177
	v_fma_f32 v178, -v53, v169, v178
	v_fma_f32 v179, -v117, v169, v179
	v_fma_f32 v176, -v82, v170, v176
	v_fma_f32 v180, -v37, v169, v180
	v_fma_f32 v181, -v101, v169, v181
	v_fma_f32 v168, -v85, v169, v168
	v_fma_f32 v177, -v134, v170, v177
	v_fma_f32 v178, -v54, v170, v178
	v_fma_f32 v176, -v83, v171, v176
	v_fma_f32 v179, -v118, v170, v179
	v_fma_f32 v180, -v38, v170, v180
	v_fma_f32 v181, -v102, v170, v181
	v_fma_f32 v182, -v17, v169, v182
	v_fma_f32 v168, -v86, v170, v168
	v_fma_f32 v177, -v135, v171, v177
	v_fma_f32 v178, -v55, v171, v178
	v_fma_f32 v179, -v119, v171, v179
	v_fma_f32 v180, -v39, v171, v180
	v_fma_f32 v169, -v18, v170, v182
	s_waitcnt lgkmcnt(4)
	v_fma_f32 v170, -v68, v172, v176
	v_fma_f32 v181, -v103, v171, v181
	v_fma_f32 v168, -v87, v171, v168
	v_fma_f32 v176, -v48, v172, v178
	v_fma_f32 v178, -v32, v172, v180
	v_fma_f32 v169, -v19, v171, v169
	v_fma_f32 v171, -v128, v172, v177
	v_fma_f32 v170, -v69, v173, v170
	v_fma_f32 v177, -v112, v172, v179
	v_fma_f32 v176, -v49, v173, v176
	v_fma_f32 v179, -v96, v172, v181
	v_fma_f32 v169, -v12, v172, v169
	v_fma_f32 v171, -v129, v173, v171
	v_fma_f32 v170, -v70, v174, v170
	v_fma_f32 v178, -v33, v173, v178
	v_fma_f32 v168, -v76, v172, v168
	v_fma_f32 v177, -v113, v173, v177
	v_fma_f32 v169, -v13, v173, v169
	v_fma_f32 v171, -v130, v174, v171
	v_fma_f32 v170, -v71, v175, v170
	v_fma_f32 v176, -v50, v174, v176
	v_fma_f32 v179, -v97, v173, v179
	v_fma_f32 v178, -v34, v174, v178
	v_fma_f32 v168, -v77, v173, v168
	v_fma_f32 v171, -v131, v175, v171
	v_fma_f32 v169, -v14, v174, v169
	s_waitcnt lgkmcnt(3)
	v_fma_f32 v170, -v60, v164, v170
	v_fma_f32 v177, -v114, v174, v177
	v_fma_f32 v176, -v51, v175, v176
	v_fma_f32 v179, -v98, v174, v179
	v_fma_f32 v178, -v35, v175, v178
	v_fma_f32 v168, -v78, v174, v168
	v_fma_f32 v169, -v15, v175, v169
	v_fma_f32 v171, -v124, v164, v171
	v_fma_f32 v170, -v61, v165, v170
	v_fma_f32 v172, -v44, v164, v176
	v_fma_f32 v174, -v28, v164, v178
	v_fma_f32 v177, -v115, v175, v177
	v_fma_f32 v179, -v99, v175, v179
	v_fma_f32 v168, -v79, v175, v168
	v_fma_f32 v171, -v125, v165, v171
	v_fma_f32 v170, -v62, v166, v170
	v_fma_f32 v172, -v45, v165, v172
	v_fma_f32 v173, -v108, v164, v177
	v_fma_f32 v175, -v92, v164, v179
	v_fma_f32 v174, -v29, v165, v174
	v_fma_f32 v169, -v8, v164, v169
	v_fma_f32 v164, -v72, v164, v168
	v_fma_f32 v171, -v126, v166, v171
	v_fma_f32 v170, -v63, v167, v170
	v_fma_f32 v173, -v109, v165, v173
	v_fma_f32 v172, -v46, v166, v172
	v_fma_f32 v175, -v93, v165, v175
	v_fma_f32 v174, -v30, v166, v174
	v_fma_f32 v168, -v9, v165, v169
	v_fma_f32 v164, -v73, v165, v164
	v_fma_f32 v171, -v127, v167, v171
	v_fma_f32 v173, -v110, v166, v173
	v_fma_f32 v172, -v47, v167, v172
	v_fma_f32 v175, -v94, v166, v175
	v_fma_f32 v165, -v10, v166, v168
	v_fma_f32 v174, -v31, v167, v174
	v_fma_f32 v164, -v74, v166, v164
	s_waitcnt lgkmcnt(2)
	v_fma_f32 v166, -v56, v160, v170
	v_fma_f32 v168, -v40, v160, v172
	v_fma_f32 v173, -v111, v167, v173
	v_fma_f32 v165, -v11, v167, v165
	v_fma_f32 v170, -v24, v160, v174
	v_fma_f32 v175, -v95, v167, v175
	v_fma_f32 v164, -v75, v167, v164
	v_fma_f32 v167, -v120, v160, v171
	v_fma_f32 v166, -v57, v161, v166
	v_fma_f32 v169, -v104, v160, v173
	v_fma_f32 v168, -v41, v161, v168
	v_fma_f32 v171, -v88, v160, v175
	v_fma_f32 v170, -v25, v161, v170
	v_fma_f32 v165, -v20, v160, v165
	v_fma_f32 v160, -v64, v160, v164
	v_fma_f32 v167, -v121, v161, v167
	v_fma_f32 v166, -v58, v162, v166
	v_fma_f32 v169, -v105, v161, v169
	v_fma_f32 v168, -v42, v162, v168
	v_fma_f32 v171, -v89, v161, v171
	v_fma_f32 v170, -v26, v162, v170
	v_fma_f32 v164, -v21, v161, v165
	v_fma_f32 v160, -v65, v161, v160
	v_fma_f32 v166, -v59, v163, v166
	v_fma_f32 v168, -v43, v163, v168
	v_fma_f32 v167, -v122, v162, v167
	v_fma_f32 v170, -v27, v163, v170
	v_fma_f32 v161, -v22, v162, v164
	v_fma_f32 v169, -v106, v162, v169
	v_fma_f32 v171, -v90, v162, v171
	s_nop 0
	s_nop 1
	v_permlane16_swap_b32 v166, v168
	v_fma_f32 v160, -v66, v162, v160
	v_fma_f32 v167, -v123, v163, v167
	v_fma_f32 v161, -v23, v163, v161
	v_fma_f32 v169, -v107, v163, v169
	v_fma_f32 v171, -v91, v163, v171
	s_nop 0
	v_add_f32_e32 v162, v166, v168
	s_nop 1
	v_permlane16_swap_b32 v170, v161
	v_fma_f32 v160, -v67, v163, v160
	s_nop 0
	v_add_f32_e32 v161, v170, v161
	s_nop 1
	v_permlane32_swap_b32 v162, v161
	s_nop 0
	v_add_f32_e32 v242, v162, v161
	v_mov_b32_e32 v240, v242
	s_nop 1
	v_permlane16_swap_b32 v242, v240
	s_nop 0
	v_mov_b32_e32 v238, v242
	v_mov_b32_e32 v236, v240
	s_nop 1
	v_permlane32_swap_b32 v242, v238
	s_nop 1
	v_permlane32_swap_b32 v240, v236
	s_nop 1
	v_permlane16_swap_b32 v167, v169
	s_nop 1
	v_permlane16_swap_b32 v171, v160
	s_nop 0
	v_add_f32_e32 v161, v167, v169
	v_add_f32_e32 v160, v171, v160
	s_nop 1
	v_permlane32_swap_b32 v161, v160
	s_nop 0
	v_add_f32_e32 v243, v161, v160
	v_mov_b32_e32 v241, v243
	s_nop 1
	v_permlane16_swap_b32 v243, v241
	s_nop 0
	v_mov_b32_e32 v239, v243
	v_mov_b32_e32 v237, v241
	s_nop 1
	v_permlane32_swap_b32 v243, v239
	s_nop 1
	v_permlane32_swap_b32 v241, v237
	ds_read_b128 v[172:175], v234 offset:512
	ds_read_b128 v[176:179], v234 offset:768
	ds_read_b128 v[180:183], v234 offset:1024
	s_waitcnt lgkmcnt(2)
; #define LAS __attribute__((address_space(3)))
; __device__ __forceinline__ float fma_s(float a, float b, float c) { float d; asm("v_fma_f32 %0, %1, %2, %3" : "=v"(d) : "v"(a), "v"(b), "v"(c)); return d; }
; __device__ __forceinline__ float mul_s(float a, float b) { float d; asm("v_mul_f32 %0, %1, %2" : "=v"(d) : "v"(a), "v"(b)); return d; }
; __device__ __forceinline__ void even_scan(const Params& p, int j, LAS unsigned char* lds, int gw, int NGW, int wave, int lane) {
;     ...
; #pragma unroll
;                 for (int c = 0; c < 16; c += 4) {
;                     const f32x4 w4 = *(const LAS f32x4*)(sb + 64 + c), b4 = *(const LAS f32x4*)(sb + 128 + c), k4 = *(const LAS f32x4*)(sb + 192 + c), r4 = *(const LAS f32x4*)(sb + 256 + c);
; #pragma unroll
;                     for (int rr = 0; rr < 4; ++rr)
; #pragma unroll
;                         for (int e = 0; e < 4; ++e) {
;                             float tL = mul_s(saL[rr], b4[e]); tL = fma_s(vv[rr], k4[e], tL); SL[rr][c + e] = fma_s(SL[rr][c + e], w4[e], tL); yL[rr] = fma_s(SL[rr][c + e], r4[e], yL[rr]);
;                             const float tP = mul_s(saP[rr], b4[e]); SP[rr][c + e] = fma_s(SP[rr][c + e], w4[e], tP); yP[rr] = fma_s(SP[rr][c + e], r4[e], yP[rr]); }
;                 }
	v_mul_f32 v160, v242, v172
	s_waitcnt lgkmcnt(1)
	v_fma_f32 v190, v218, v176, v160
	ds_read_b128 v[186:189], v234 offset:256
	ds_read_b128 v[168:171], v234 offset:272
	ds_read_b128 v[164:167], v234 offset:288
	ds_read_b128 v[160:163], v234 offset:304
	v_mul_f32 v244, v242, v173
	v_mul_f32 v191, v243, v172
	v_mul_f32 v245, v240, v173
	s_waitcnt lgkmcnt(3)
	v_fma_f32 v80, v80, v186, v190
	v_fma_f32 v244, v218, v177, v244
	v_fma_f32 v132, v132, v186, v191
	v_fma_f32 v245, v219, v177, v245
	v_fma_f32 v190, v80, v180, v185
	v_fma_f32 v81, v81, v187, v244
	v_mul_f32 v244, v243, v173
	v_fma_f32 v191, v132, v180, v185
	v_fma_f32 v53, v53, v187, v245
	v_mul_f32 v245, v241, v173
	v_fma_f32 v133, v133, v187, v244
	v_mul_f32 v244, v242, v174
	v_fma_f32 v117, v117, v187, v245
	v_mul_f32 v245, v240, v174
	v_fma_f32 v190, v81, v181, v190
	v_fma_f32 v244, v218, v178, v244
	v_fma_f32 v191, v133, v181, v191
	v_fma_f32 v245, v219, v178, v245
	v_fma_f32 v82, v82, v188, v244
	v_mul_f32 v244, v243, v174
	v_fma_f32 v54, v54, v188, v245
	v_mul_f32 v245, v241, v174
	v_fma_f32 v134, v134, v188, v244
	v_mul_f32 v244, v242, v175
	v_fma_f32 v118, v118, v188, v245
	v_mul_f32 v245, v240, v175
	v_fma_f32 v190, v82, v182, v190
	v_fma_f32 v191, v134, v182, v191
	v_fma_f32 v244, v218, v179, v244
	v_fma_f32 v245, v219, v179, v245
	v_fma_f32 v83, v83, v189, v244
	v_mul_f32 v244, v243, v175
	v_fma_f32 v55, v55, v189, v245
	v_mul_f32 v245, v238, v173
	v_fma_f32 v135, v135, v189, v244
	v_fma_f32 v245, v216, v177, v245
	v_mul_f32 v244, v241, v172
	v_fma_f32 v190, v83, v183, v190
	v_fma_f32 v250, v135, v183, v191
	v_mul_f32 v191, v240, v172
	v_fma_f32 v37, v37, v187, v245
	v_mul_f32 v245, v239, v173
	v_fma_f32 v116, v116, v186, v244
	v_fma_f32 v191, v219, v176, v191
	v_fma_f32 v101, v101, v187, v245
	v_mul_f32 v245, v238, v174
	v_fma_f32 v244, v116, v180, v185
	v_fma_f32 v52, v52, v186, v191
	v_fma_f32 v245, v216, v178, v245
	v_fma_f32 v244, v117, v181, v244
	v_fma_f32 v191, v52, v180, v185
	v_fma_f32 v38, v38, v188, v245
	v_mul_f32 v245, v239, v174
	v_fma_f32 v244, v118, v182, v244
	v_fma_f32 v191, v53, v181, v191
	v_fma_f32 v102, v102, v188, v245
	v_mul_f32 v245, v238, v175
	v_fma_f32 v191, v54, v182, v191
	v_fma_f32 v245, v216, v179, v245
	v_fma_f32 v249, v55, v183, v191
	v_mul_f32 v191, v241, v175
	v_fma_f32 v39, v39, v189, v245
	v_fma_f32 v119, v119, v189, v191
	v_mul_f32 v191, v238, v172
	v_fma_f32 v191, v216, v176, v191
	v_fma_f32 v248, v119, v183, v244
	v_mul_f32 v244, v239, v172
	v_fma_f32 v36, v36, v186, v191
	v_fma_f32 v100, v100, v186, v244
	v_fma_f32 v191, v36, v180, v185
	v_fma_f32 v244, v100, v180, v185
	v_fma_f32 v191, v37, v181, v191
	v_fma_f32 v244, v101, v181, v244
	v_fma_f32 v191, v38, v182, v191
	v_fma_f32 v244, v102, v182, v244
	v_fma_f32 v247, v39, v183, v191
	v_mul_f32 v191, v239, v175
	v_fma_f32 v103, v103, v189, v191
	v_mul_f32 v191, v236, v172
	v_mul_f32 v172, v237, v172
	v_fma_f32 v176, v217, v176, v191
	v_fma_f32 v84, v84, v186, v172
	v_fma_f32 v246, v103, v183, v244
	v_fma_f32 v16, v16, v186, v176
	v_fma_f32 v172, v84, v180, v185
	v_fma_f32 v176, v16, v180, v185
	v_mul_f32 v180, v236, v173
	v_mul_f32 v173, v237, v173
	v_fma_f32 v85, v85, v187, v173
	v_mul_f32 v173, v236, v174
	v_mul_f32 v174, v237, v174
	v_fma_f32 v177, v217, v177, v180
	v_fma_f32 v173, v217, v178, v173
	v_fma_f32 v17, v17, v187, v177
	v_fma_f32 v172, v85, v181, v172
	v_fma_f32 v86, v86, v188, v174
	v_mul_f32 v174, v236, v175
	v_fma_f32 v176, v17, v181, v176
	v_fma_f32 v18, v18, v188, v173
	v_fma_f32 v172, v86, v182, v172
	v_fma_f32 v174, v217, v179, v174
	v_fma_f32 v173, v18, v182, v176
	v_fma_f32 v19, v19, v189, v174
	v_fma_f32 v245, v19, v183, v173
	v_mul_f32 v173, v237, v175
	v_fma_f32 v87, v87, v189, v173
	v_fma_f32 v244, v87, v183, v172
	ds_read_b128 v[172:175], v234 offset:528
	ds_read_b128 v[176:179], v234 offset:784
	ds_read_b128 v[180:183], v234 offset:1040
	s_waitcnt lgkmcnt(2)
	v_mul_f32 v188, v242, v173
	s_waitcnt lgkmcnt(1)
	v_fma_f32 v188, v218, v177, v188
	v_mul_f32 v186, v242, v172
	v_mul_f32 v187, v243, v172
	v_fma_f32 v69, v69, v169, v188
	v_mul_f32 v188, v243, v173
	v_fma_f32 v186, v218, v176, v186
	v_fma_f32 v128, v128, v168, v187
	v_fma_f32 v129, v129, v169, v188
	v_mul_f32 v188, v242, v174
	v_fma_f32 v68, v68, v168, v186
	s_waitcnt lgkmcnt(0)
; #define LAS __attribute__((address_space(3)))
; __device__ __forceinline__ float fma_s(float a, float b, float c) { float d; asm("v_fma_f32 %0, %1, %2, %3" : "=v"(d) : "v"(a), "v"(b), "v"(c)); return d; }
; __device__ __forceinline__ float mul_s(float a, float b) { float d; asm("v_mul_f32 %0, %1, %2" : "=v"(d) : "v"(a), "v"(b)); return d; }
; __device__ __forceinline__ void even_scan(const Params& p, int j, LAS unsigned char* lds, int gw, int NGW, int wave, int lane) {
;     ...
; #pragma unroll
;                 for (int c = 0; c < 16; c += 4) {
;                     const f32x4 w4 = *(const LAS f32x4*)(sb + 64 + c), b4 = *(const LAS f32x4*)(sb + 128 + c), k4 = *(const LAS f32x4*)(sb + 192 + c), r4 = *(const LAS f32x4*)(sb + 256 + c);
; #pragma unroll
;                     for (int rr = 0; rr < 4; ++rr)
; #pragma unroll
;                         for (int e = 0; e < 4; ++e) {
;                             float tL = mul_s(saL[rr], b4[e]); tL = fma_s(vv[rr], k4[e], tL); SL[rr][c + e] = fma_s(SL[rr][c + e], w4[e], tL); yL[rr] = fma_s(SL[rr][c + e], r4[e], yL[rr]);
;                             const float tP = mul_s(saP[rr], b4[e]); SP[rr][c + e] = fma_s(SP[rr][c + e], w4[e], tP); yP[rr] = fma_s(SP[rr][c + e], r4[e], yP[rr]); }
;                 }
	v_fma_f32 v187, v128, v180, v250
	v_fma_f32 v188, v218, v178, v188
	v_fma_f32 v186, v68, v180, v190
	v_fma_f32 v187, v129, v181, v187
	v_fma_f32 v70, v70, v170, v188
	v_mul_f32 v188, v243, v174
	v_fma_f32 v186, v69, v181, v186
	v_fma_f32 v130, v130, v170, v188
	v_mul_f32 v188, v242, v175
	v_fma_f32 v186, v70, v182, v186
	v_fma_f32 v188, v218, v179, v188
	v_fma_f32 v187, v130, v182, v187
	v_fma_f32 v71, v71, v171, v188
	v_mul_f32 v188, v240, v173
	v_fma_f32 v188, v219, v177, v188
	v_fma_f32 v190, v71, v183, v186
	v_mul_f32 v186, v243, v175
	v_fma_f32 v49, v49, v169, v188
	v_mul_f32 v188, v241, v173
	v_fma_f32 v131, v131, v171, v186
	v_mul_f32 v186, v240, v172
	v_fma_f32 v113, v113, v169, v188
	v_mul_f32 v188, v240, v174
	v_fma_f32 v186, v219, v176, v186
	v_fma_f32 v191, v131, v183, v187
	v_mul_f32 v187, v241, v172
	v_fma_f32 v188, v219, v178, v188
	v_fma_f32 v48, v48, v168, v186
	v_fma_f32 v112, v112, v168, v187
	v_fma_f32 v50, v50, v170, v188
	v_mul_f32 v188, v241, v174
	v_fma_f32 v186, v48, v180, v249
	v_fma_f32 v187, v112, v180, v248
	v_fma_f32 v114, v114, v170, v188
	v_mul_f32 v188, v240, v175
	v_fma_f32 v186, v49, v181, v186
	v_fma_f32 v187, v113, v181, v187
	v_fma_f32 v188, v219, v179, v188
	v_fma_f32 v186, v50, v182, v186
	v_fma_f32 v187, v114, v182, v187
	v_fma_f32 v51, v51, v171, v188
	v_mul_f32 v188, v238, v173
	v_fma_f32 v248, v51, v183, v186
	v_mul_f32 v186, v241, v175
	v_fma_f32 v188, v216, v177, v188
	v_fma_f32 v115, v115, v171, v186
	v_mul_f32 v186, v238, v172
	v_fma_f32 v33, v33, v169, v188
	v_mul_f32 v188, v239, v173
	v_fma_f32 v186, v216, v176, v186
	v_fma_f32 v97, v97, v169, v188
	v_mul_f32 v188, v238, v174
	v_fma_f32 v249, v115, v183, v187
	v_mul_f32 v187, v239, v172
	v_fma_f32 v32, v32, v168, v186
	v_fma_f32 v188, v216, v178, v188
	v_fma_f32 v96, v96, v168, v187
	v_fma_f32 v186, v32, v180, v247
	v_fma_f32 v34, v34, v170, v188
	v_mul_f32 v188, v239, v174
	v_fma_f32 v187, v96, v180, v246
	v_fma_f32 v186, v33, v181, v186
	v_fma_f32 v98, v98, v170, v188
	v_mul_f32 v188, v238, v175
	v_fma_f32 v187, v97, v181, v187
	v_fma_f32 v186, v34, v182, v186
	v_fma_f32 v188, v216, v179, v188
	v_fma_f32 v187, v98, v182, v187
	v_fma_f32 v35, v35, v171, v188
	v_fma_f32 v246, v35, v183, v186
	v_mul_f32 v186, v239, v175
	v_fma_f32 v99, v99, v171, v186
	v_mul_f32 v186, v236, v172
	v_mul_f32 v172, v237, v172
	v_fma_f32 v76, v76, v168, v172
	v_mul_f32 v172, v236, v173
	v_fma_f32 v176, v217, v176, v186
	v_mul_f32 v173, v237, v173
	v_fma_f32 v247, v99, v183, v187
	v_fma_f32 v172, v217, v177, v172
	v_fma_f32 v77, v77, v169, v173
	v_fma_f32 v12, v12, v168, v176
	v_fma_f32 v168, v76, v180, v244
	v_fma_f32 v13, v13, v169, v172
	v_mul_f32 v169, v236, v174
	v_fma_f32 v176, v12, v180, v245
	v_fma_f32 v168, v77, v181, v168
	v_fma_f32 v172, v13, v181, v176
	v_fma_f32 v169, v217, v178, v169
	v_fma_f32 v14, v14, v170, v169
	v_fma_f32 v169, v14, v182, v172
	v_mul_f32 v172, v237, v174
	v_fma_f32 v78, v78, v170, v172
	v_mul_f32 v170, v236, v175
	v_fma_f32 v168, v78, v182, v168
	v_fma_f32 v170, v217, v179, v170
	v_fma_f32 v15, v15, v171, v170
	v_fma_f32 v176, v15, v183, v169
	v_mul_f32 v169, v237, v175
	v_fma_f32 v79, v79, v171, v169
	v_fma_f32 v177, v79, v183, v168
	ds_read_b128 v[168:171], v234 offset:544
	ds_read_b128 v[172:175], v234 offset:800
	ds_read_b128 v[186:189], v234 offset:1056
	s_waitcnt lgkmcnt(2)
	v_mul_f32 v180, v242, v169
	s_waitcnt lgkmcnt(1)
	v_fma_f32 v180, v218, v173, v180
	v_mul_f32 v178, v242, v168
	v_mul_f32 v179, v243, v168
	v_fma_f32 v61, v61, v165, v180
	v_mul_f32 v180, v243, v169
	v_fma_f32 v178, v218, v172, v178
	v_fma_f32 v124, v124, v164, v179
	v_fma_f32 v125, v125, v165, v180
	v_mul_f32 v180, v242, v170
	v_fma_f32 v60, v60, v164, v178
	s_waitcnt lgkmcnt(0)
	v_fma_f32 v179, v124, v186, v191
	v_fma_f32 v180, v218, v174, v180
	v_fma_f32 v178, v60, v186, v190
	v_fma_f32 v179, v125, v187, v179
	v_mul_f32 v190, v238, v169
	v_fma_f32 v62, v62, v166, v180
	v_mul_f32 v180, v243, v170
	v_fma_f32 v178, v61, v187, v178
	v_fma_f32 v190, v216, v173, v190
	v_fma_f32 v126, v126, v166, v180
	v_mul_f32 v180, v242, v171
	v_fma_f32 v178, v62, v188, v178
	v_fma_f32 v29, v29, v165, v190
	v_mul_f32 v190, v239, v169
	v_fma_f32 v180, v218, v175, v180
	v_fma_f32 v179, v126, v188, v179
	v_fma_f32 v93, v93, v165, v190
	v_mul_f32 v190, v238, v170
	v_fma_f32 v63, v63, v167, v180
	v_mul_f32 v180, v240, v169
	v_fma_f32 v190, v216, v174, v190
	v_fma_f32 v183, v63, v189, v178
	v_mul_f32 v178, v243, v171
	v_fma_f32 v180, v219, v173, v180
	v_fma_f32 v30, v30, v166, v190
	v_mul_f32 v190, v239, v170
	v_fma_f32 v127, v127, v167, v178
	v_mul_f32 v178, v240, v168
	v_fma_f32 v45, v45, v165, v180
	v_mul_f32 v180, v241, v169
	v_fma_f32 v94, v94, v166, v190
	v_fma_f32 v178, v219, v172, v178
	v_fma_f32 v109, v109, v165, v180
	v_mul_f32 v180, v240, v170
	v_fma_f32 v182, v127, v189, v179
	v_mul_f32 v179, v241, v168
	v_fma_f32 v44, v44, v164, v178
	v_fma_f32 v180, v219, v174, v180
	v_fma_f32 v108, v108, v164, v179
	v_fma_f32 v178, v44, v186, v248
	v_fma_f32 v179, v108, v186, v249
	v_fma_f32 v46, v46, v166, v180
	v_mul_f32 v180, v241, v170
	v_fma_f32 v178, v45, v187, v178
	v_fma_f32 v179, v109, v187, v179
	v_fma_f32 v110, v110, v166, v180
	v_mul_f32 v180, v240, v171
	v_fma_f32 v178, v46, v188, v178
	v_fma_f32 v179, v110, v188, v179
	v_fma_f32 v180, v219, v175, v180
	v_fma_f32 v47, v47, v167, v180
	v_fma_f32 v181, v47, v189, v178
	v_mul_f32 v178, v241, v171
	v_fma_f32 v111, v111, v167, v178
	v_mul_f32 v178, v238, v168
	v_fma_f32 v180, v111, v189, v179
	v_mul_f32 v179, v239, v168
	v_fma_f32 v178, v216, v172, v178
	v_fma_f32 v92, v92, v164, v179
	v_fma_f32 v28, v28, v164, v178
; #define LAS __attribute__((address_space(3)))
; __device__ __forceinline__ void swap16_(float& a, float& b) { asm volatile("s_nop 1\n\tv_permlane16_swap_b32 %0, %1" : "+v"(a), "+v"(b)); }
; __device__ __forceinline__ void swap32_(float& a, float& b) { asm volatile("s_nop 1\n\tv_permlane32_swap_b32 %0, %1" : "+v"(a), "+v"(b)); }
; __device__ __forceinline__ float fma_s(float a, float b, float c) { float d; asm("v_fma_f32 %0, %1, %2, %3" : "=v"(d) : "v"(a), "v"(b), "v"(c)); return d; }
; __device__ __forceinline__ float mul_s(float a, float b) { float d; asm("v_mul_f32 %0, %1, %2" : "=v"(d) : "v"(a), "v"(b)); return d; }
; __device__ __forceinline__ void even_scan(const Params& p, int j, LAS unsigned char* lds, int gw, int NGW, int wave, int lane) {
;     ...
;                 for (int c = 0; c < 16; c += 4) {
;                     const f32x4 w4 = *(const LAS f32x4*)(sb + 64 + c), b4 = *(const LAS f32x4*)(sb + 128 + c), k4 = *(const LAS f32x4*)(sb + 192 + c), r4 = *(const LAS f32x4*)(sb + 256 + c);
; #pragma unroll
;                     for (int rr = 0; rr < 4; ++rr)
; #pragma unroll
;                         for (int e = 0; e < 4; ++e) {
;                             float tL = mul_s(saL[rr], b4[e]); tL = fma_s(vv[rr], k4[e], tL); SL[rr][c + e] = fma_s(SL[rr][c + e], w4[e], tL); yL[rr] = fma_s(SL[rr][c + e], r4[e], yL[rr]);
;                             const float tP = mul_s(saP[rr], b4[e]); SP[rr][c + e] = fma_s(SP[rr][c + e], w4[e], tP); yP[rr] = fma_s(SP[rr][c + e], r4[e], yP[rr]); }
;                 }
;                 float yoL, yoP;
;                 { float a = yL[0], b = yL[1], c = yL[2], d = yL[3]; swap16_(a, b); swap16_(c, d); float s01 = a + b, s23 = c + d; swap32_(s01, s23); yoL = s01 + s23; }
;                 { float a = yP[0], b = yP[1], c = yP[2], d = yP[3]; swap16_(a, b); swap16_(c, d); float s01 = a + b, s23 = c + d; swap32_(s01, s23); yoP = s01 + s23; }
;                 const size_t oo = base + (size_t)(st * TS + s) * 512 + lane;
;                 YL[oo] = yoL; if (!samp) QQ[oo] = yoP;
; #pragma unroll
;                 for (int c = 0; c < CPS; ++c) { const int li = cli + c * NGW * 64;
;                     if (li < KVC_N2 && ((li >> 8) & 2047) >= 8) __builtin_nontemporal_store(cbuf[c], (f32x4*)((char*)(csrc + c * NGW * 64) + cdelta)); }
;                 cli += cstride; csrc += cstride; ++cstep;
	v_fma_f32 v179, v92, v186, v247
	v_fma_f32 v178, v28, v186, v246
	v_fma_f32 v179, v93, v187, v179
	v_fma_f32 v178, v29, v187, v178
	v_fma_f32 v190, v94, v188, v179
	v_mul_f32 v179, v238, v171
	v_fma_f32 v178, v30, v188, v178
	v_fma_f32 v179, v216, v175, v179
	v_fma_f32 v31, v31, v167, v179
	v_fma_f32 v179, v31, v189, v178
	v_mul_f32 v178, v239, v171
	v_fma_f32 v95, v95, v167, v178
	v_fma_f32 v178, v95, v189, v190
	v_mul_f32 v190, v236, v168
	v_mul_f32 v168, v237, v168
	v_fma_f32 v72, v72, v164, v168
	v_mul_f32 v168, v236, v169
	v_fma_f32 v172, v217, v172, v190
	v_mul_f32 v169, v237, v169
	v_fma_f32 v168, v217, v173, v168
	v_fma_f32 v73, v73, v165, v169
	v_fma_f32 v8, v8, v164, v172
	v_fma_f32 v164, v72, v186, v177
	v_fma_f32 v9, v9, v165, v168
	v_mul_f32 v165, v236, v170
	v_fma_f32 v172, v8, v186, v176
	v_fma_f32 v164, v73, v187, v164
	v_fma_f32 v168, v9, v187, v172
	v_fma_f32 v165, v217, v174, v165
	v_fma_f32 v10, v10, v166, v165
	v_fma_f32 v165, v10, v188, v168
	v_mul_f32 v168, v237, v170
	v_fma_f32 v74, v74, v166, v168
	v_mul_f32 v166, v236, v171
	v_fma_f32 v164, v74, v188, v164
	v_fma_f32 v166, v217, v175, v166
	v_fma_f32 v11, v11, v167, v166
	v_fma_f32 v177, v11, v189, v165
	v_mul_f32 v165, v237, v171
	v_fma_f32 v75, v75, v167, v165
	v_fma_f32 v176, v75, v189, v164
	ds_read_b128 v[164:167], v234 offset:560
	ds_read_b128 v[172:175], v234 offset:816
	ds_read_b128 v[168:171], v234 offset:1072
	s_waitcnt lgkmcnt(2)
	v_mul_f32 v186, v242, v164
	s_waitcnt lgkmcnt(1)
	v_fma_f32 v186, v218, v172, v186
	v_fma_f32 v56, v56, v160, v186
	v_mul_f32 v186, v243, v164
	v_fma_f32 v120, v120, v160, v186
	v_mul_f32 v186, v242, v165
	s_waitcnt lgkmcnt(0)
	v_fma_f32 v183, v56, v168, v183
	v_fma_f32 v186, v218, v173, v186
	v_fma_f32 v182, v120, v168, v182
	v_fma_f32 v57, v57, v161, v186
	v_mul_f32 v186, v243, v165
	v_fma_f32 v121, v121, v161, v186
	v_mul_f32 v186, v242, v166
	v_fma_f32 v183, v57, v169, v183
	v_fma_f32 v186, v218, v174, v186
	v_fma_f32 v182, v121, v169, v182
	v_fma_f32 v58, v58, v162, v186
	v_mul_f32 v186, v243, v166
	v_fma_f32 v122, v122, v162, v186
	v_mul_f32 v186, v242, v167
	v_fma_f32 v183, v58, v170, v183
	v_fma_f32 v186, v218, v175, v186
	v_fma_f32 v182, v122, v170, v182
	v_fma_f32 v59, v59, v163, v186
	v_mul_f32 v186, v243, v167
	v_fma_f32 v123, v123, v163, v186
	v_mul_f32 v186, v240, v164
	v_fma_f32 v183, v59, v171, v183
	v_fma_f32 v186, v219, v172, v186
	v_fma_f32 v182, v123, v171, v182
	v_fma_f32 v40, v40, v160, v186
	v_mul_f32 v186, v241, v164
	v_fma_f32 v104, v104, v160, v186
	v_mul_f32 v186, v240, v165
	v_fma_f32 v181, v40, v168, v181
	v_fma_f32 v186, v219, v173, v186
	v_fma_f32 v180, v104, v168, v180
	v_fma_f32 v41, v41, v161, v186
	v_mul_f32 v186, v241, v165
	v_fma_f32 v105, v105, v161, v186
	v_mul_f32 v186, v240, v166
	v_fma_f32 v181, v41, v169, v181
	v_fma_f32 v186, v219, v174, v186
	v_fma_f32 v180, v105, v169, v180
	v_fma_f32 v42, v42, v162, v186
	v_mul_f32 v186, v241, v166
	v_fma_f32 v106, v106, v162, v186
	v_mul_f32 v186, v240, v167
	v_fma_f32 v181, v42, v170, v181
	v_fma_f32 v186, v219, v175, v186
	v_fma_f32 v180, v106, v170, v180
	v_fma_f32 v43, v43, v163, v186
	v_mul_f32 v186, v241, v167
	v_fma_f32 v107, v107, v163, v186
	v_mul_f32 v186, v238, v164
	v_fma_f32 v181, v43, v171, v181
	v_fma_f32 v186, v216, v172, v186
	s_nop 1
	v_permlane16_swap_b32 v183, v181
	v_fma_f32 v180, v107, v171, v180
	v_fma_f32 v24, v24, v160, v186
	v_mul_f32 v186, v239, v164
	v_fma_f32 v88, v88, v160, v186
	v_mul_f32 v186, v238, v165
	v_fma_f32 v179, v24, v168, v179
	v_fma_f32 v186, v216, v173, v186
	v_fma_f32 v178, v88, v168, v178
	v_fma_f32 v25, v25, v161, v186
	v_mul_f32 v186, v239, v165
	v_fma_f32 v89, v89, v161, v186
	v_mul_f32 v186, v238, v166
	v_fma_f32 v179, v25, v169, v179
	v_fma_f32 v186, v216, v174, v186
	v_fma_f32 v178, v89, v169, v178
	v_fma_f32 v26, v26, v162, v186
	v_mul_f32 v186, v239, v166
	v_fma_f32 v90, v90, v162, v186
	v_mul_f32 v186, v238, v167
	v_fma_f32 v179, v26, v170, v179
	v_fma_f32 v186, v216, v175, v186
	v_fma_f32 v178, v90, v170, v178
	v_fma_f32 v27, v27, v163, v186
	v_mul_f32 v186, v239, v167
	v_fma_f32 v91, v91, v163, v186
	v_mul_f32 v186, v236, v164
	v_mul_f32 v164, v237, v164
	v_fma_f32 v179, v27, v171, v179
	v_fma_f32 v64, v64, v160, v164
	v_mul_f32 v164, v236, v165
	v_fma_f32 v172, v217, v172, v186
	v_mul_f32 v165, v237, v165
	v_fma_f32 v178, v91, v171, v178
	v_fma_f32 v164, v217, v173, v164
	v_fma_f32 v65, v65, v161, v165
	v_fma_f32 v20, v20, v160, v172
	v_fma_f32 v160, v64, v168, v176
	v_fma_f32 v21, v21, v161, v164
	v_mul_f32 v161, v236, v166
	v_fma_f32 v172, v20, v168, v177
	v_fma_f32 v160, v65, v169, v160
	v_fma_f32 v164, v21, v169, v172
	v_fma_f32 v161, v217, v174, v161
	v_fma_f32 v22, v22, v162, v161
	v_fma_f32 v161, v22, v170, v164
	v_mul_f32 v164, v237, v166
	v_fma_f32 v66, v66, v162, v164
	v_mul_f32 v162, v236, v167
	v_fma_f32 v162, v217, v175, v162
	v_fma_f32 v160, v66, v170, v160
	v_fma_f32 v23, v23, v163, v162
	v_mul_f32 v162, v237, v167
	v_fma_f32 v161, v23, v171, v161
	v_fma_f32 v67, v67, v163, v162
	s_nop 0
	s_nop 1
	v_permlane16_swap_b32 v179, v161
	v_fma_f32 v162, v67, v171, v160
	v_add_f32_e32 v160, v183, v181
	v_add_f32_e32 v161, v179, v161
	s_nop 1
	v_permlane32_swap_b32 v160, v161
	s_nop 1
	v_permlane16_swap_b32 v182, v180
	s_nop 1
	v_permlane16_swap_b32 v178, v162
	s_nop 0
	v_add_f32_e32 v164, v160, v161
	v_add_f32_e32 v161, v178, v162
	v_lshl_add_u64 v[162:163], v[206:207], 0, s[38:39]
	v_add_co_u32_e32 v162, vcc, 0x37500000, v162
	v_add_f32_e32 v160, v182, v180
	s_nop 0
	v_addc_co_u32_e32 v163, vcc, 0, v163, vcc
	s_nop 1
	v_permlane32_swap_b32 v160, v161
	global_store_dword v[162:163], v164, off
	v_cndmask_b32_e64 v162, 0, 1, s[62:63]
	v_cmp_ne_u32_e64 s[36:37], 1, v162
	s_andn2_b64 vcc, exec, s[62:63]
	s_cbranch_vccz .LBB0_1338
	s_and_saveexec_b64 s[24:25], s[26:27]
	s_cbranch_execnz .LBB0_1339
